# v081 + GEMM accumulator zeroing with v_pk_mov_b32 pairs (441 fewer VALU per tile set)
# speedup vs baseline: 1.0043x; 1.0043x over previous
; template <class Epi, class Sched, bool ALIGN_EPI = false, bool SP2 = false>
; __device__ __forceinline__ void gemm_phase(PG8_LAS unsigned char* lds, const Gemm g, const Sched& S, const Epi& E, const int wave0) {
;     ...
;         for (int t = 0; t < nt; t += 2) {
;             const bool last = (t == nt - 2);
;             const char* a1 = cA + (size_t)(t + 1) * kstep;
;             const char* a2 = last ? nA : cA + (size_t)(t + 2) * kstep; const char* b2 = last ? nB : cB + (size_t)(t + 2) * kstep;
;             const char* a3 = a2 + kstep; const char* b3 = b2 + kstep;
;     ...
; #pragma unroll
;         for (int a = 0; a < 2; ++a)
; #pragma unroll
;             for (int b = 0; b < 2; ++b)
; #pragma unroll
;                 for (int m = 0; m < 4; ++m)
; #pragma unroll
;                     for (int n = 0; n < 2; ++n) acc[a][b][m][n] = (f32x4){0.f, 0.f, 0.f, 0.f};
.LBB0_253:
	s_add_u32 s6, s50, 0x100
	s_addc_u32 s7, s51, 0
	s_add_u32 s43, s48, 0x100
	s_addc_u32 s95, s49, 0
	s_add_u32 s48, s50, 0x80080
	v_mov_b32_e32 v0, 0
	s_addc_u32 s49, s51, 0
	s_mov_b32 s96, -2
	v_mov_b32_e32 v1, v0
	v_pk_mov_b32 v[2:3], v[0:1], v[0:1]
	v_pk_mov_b32 v[4:5], v[0:1], v[0:1]
	v_pk_mov_b32 v[6:7], v[0:1], v[0:1]
	v_pk_mov_b32 v[8:9], v[0:1], v[0:1]
	v_pk_mov_b32 v[10:11], v[0:1], v[0:1]
	v_pk_mov_b32 v[16:17], v[0:1], v[0:1]
	v_pk_mov_b32 v[18:19], v[0:1], v[0:1]
	v_pk_mov_b32 v[24:25], v[0:1], v[0:1]
	v_pk_mov_b32 v[26:27], v[0:1], v[0:1]
	v_pk_mov_b32 v[32:33], v[0:1], v[0:1]
	v_pk_mov_b32 v[34:35], v[0:1], v[0:1]
	v_pk_mov_b32 v[40:41], v[0:1], v[0:1]
	v_pk_mov_b32 v[42:43], v[0:1], v[0:1]
	v_pk_mov_b32 v[48:49], v[0:1], v[0:1]
	v_pk_mov_b32 v[50:51], v[0:1], v[0:1]
	v_pk_mov_b32 v[12:13], v[0:1], v[0:1]
	v_pk_mov_b32 v[14:15], v[0:1], v[0:1]
	v_pk_mov_b32 v[20:21], v[0:1], v[0:1]
	v_pk_mov_b32 v[22:23], v[0:1], v[0:1]
	v_pk_mov_b32 v[28:29], v[0:1], v[0:1]
	v_pk_mov_b32 v[30:31], v[0:1], v[0:1]
	v_pk_mov_b32 v[36:37], v[0:1], v[0:1]
	v_pk_mov_b32 v[38:39], v[0:1], v[0:1]
	v_pk_mov_b32 v[44:45], v[0:1], v[0:1]
	v_pk_mov_b32 v[46:47], v[0:1], v[0:1]
	v_pk_mov_b32 v[52:53], v[0:1], v[0:1]
	v_pk_mov_b32 v[54:55], v[0:1], v[0:1]
	v_pk_mov_b32 v[56:57], v[0:1], v[0:1]
	v_pk_mov_b32 v[58:59], v[0:1], v[0:1]
	v_pk_mov_b32 v[60:61], v[0:1], v[0:1]
	v_pk_mov_b32 v[62:63], v[0:1], v[0:1]
	v_pk_mov_b32 v[64:65], v[0:1], v[0:1]
	v_pk_mov_b32 v[66:67], v[0:1], v[0:1]
	v_pk_mov_b32 v[68:69], v[0:1], v[0:1]
	v_pk_mov_b32 v[70:71], v[0:1], v[0:1]
	v_pk_mov_b32 v[72:73], v[0:1], v[0:1]
	v_pk_mov_b32 v[74:75], v[0:1], v[0:1]
	v_pk_mov_b32 v[80:81], v[0:1], v[0:1]
	v_pk_mov_b32 v[82:83], v[0:1], v[0:1]
	v_pk_mov_b32 v[88:89], v[0:1], v[0:1]
	v_pk_mov_b32 v[90:91], v[0:1], v[0:1]
	v_pk_mov_b32 v[96:97], v[0:1], v[0:1]
	v_pk_mov_b32 v[98:99], v[0:1], v[0:1]
	v_pk_mov_b32 v[104:105], v[0:1], v[0:1]
	v_pk_mov_b32 v[106:107], v[0:1], v[0:1]
	v_pk_mov_b32 v[112:113], v[0:1], v[0:1]
	v_pk_mov_b32 v[114:115], v[0:1], v[0:1]
	v_pk_mov_b32 v[76:77], v[0:1], v[0:1]
	v_pk_mov_b32 v[78:79], v[0:1], v[0:1]
	v_pk_mov_b32 v[84:85], v[0:1], v[0:1]
	v_pk_mov_b32 v[86:87], v[0:1], v[0:1]
	v_pk_mov_b32 v[92:93], v[0:1], v[0:1]
	v_pk_mov_b32 v[94:95], v[0:1], v[0:1]
	v_pk_mov_b32 v[100:101], v[0:1], v[0:1]
	v_pk_mov_b32 v[102:103], v[0:1], v[0:1]
	v_pk_mov_b32 v[108:109], v[0:1], v[0:1]
	v_pk_mov_b32 v[110:111], v[0:1], v[0:1]
	v_pk_mov_b32 v[116:117], v[0:1], v[0:1]
	v_pk_mov_b32 v[118:119], v[0:1], v[0:1]
	v_pk_mov_b32 v[120:121], v[0:1], v[0:1]
	v_pk_mov_b32 v[122:123], v[0:1], v[0:1]
	v_pk_mov_b32 v[124:125], v[0:1], v[0:1]
	v_pk_mov_b32 v[126:127], v[0:1], v[0:1]

; template <class Epi, class Sched, bool ALIGN_EPI = false, bool SP2 = false>
; __device__ __forceinline__ void gemm_phase(PG8_LAS unsigned char* lds, const Gemm g, const Sched& S, const Epi& E, const int wave0) {
;     ...
;         for (int t = 0; t < nt; t += 2) {
;             const bool last = (t == nt - 2);
;             const char* a1 = cA + (size_t)(t + 1) * kstep;
;             const char* a2 = last ? nA : cA + (size_t)(t + 2) * kstep; const char* b2 = last ? nB : cB + (size_t)(t + 2) * kstep;
;             const char* a3 = a2 + kstep; const char* b3 = b2 + kstep;
;     ...
; #pragma unroll
;         for (int a = 0; a < 2; ++a)
; #pragma unroll
;             for (int b = 0; b < 2; ++b)
; #pragma unroll
;                 for (int m = 0; m < 4; ++m)
; #pragma unroll
;                     for (int n = 0; n < 2; ++n) acc[a][b][m][n] = (f32x4){0.f, 0.f, 0.f, 0.f};
.LBB0_658:
	s_add_u32 s97, s48, 0x100
	s_addc_u32 vcc_lo, s49, 0
	s_add_u32 vcc_hi, s46, 0x100
	s_addc_u32 s6, s47, 0
	s_add_u32 s46, s48, 0xb0080
	v_mov_b32_e32 v0, 0
	s_addc_u32 s47, s49, 0
	s_mov_b32 s7, -2
	v_mov_b32_e32 v1, v0
	v_pk_mov_b32 v[2:3], v[0:1], v[0:1]
	v_pk_mov_b32 v[4:5], v[0:1], v[0:1]
	v_pk_mov_b32 v[6:7], v[0:1], v[0:1]
	v_pk_mov_b32 v[8:9], v[0:1], v[0:1]
	v_pk_mov_b32 v[10:11], v[0:1], v[0:1]
	v_pk_mov_b32 v[16:17], v[0:1], v[0:1]
	v_pk_mov_b32 v[18:19], v[0:1], v[0:1]
	v_pk_mov_b32 v[24:25], v[0:1], v[0:1]
	v_pk_mov_b32 v[26:27], v[0:1], v[0:1]
	v_pk_mov_b32 v[32:33], v[0:1], v[0:1]
	v_pk_mov_b32 v[34:35], v[0:1], v[0:1]
	v_pk_mov_b32 v[40:41], v[0:1], v[0:1]
	v_pk_mov_b32 v[42:43], v[0:1], v[0:1]
	v_pk_mov_b32 v[48:49], v[0:1], v[0:1]
	v_pk_mov_b32 v[50:51], v[0:1], v[0:1]
	v_pk_mov_b32 v[12:13], v[0:1], v[0:1]
	v_pk_mov_b32 v[14:15], v[0:1], v[0:1]
	v_pk_mov_b32 v[20:21], v[0:1], v[0:1]
	v_pk_mov_b32 v[22:23], v[0:1], v[0:1]
	v_pk_mov_b32 v[28:29], v[0:1], v[0:1]
	v_pk_mov_b32 v[30:31], v[0:1], v[0:1]
	v_pk_mov_b32 v[36:37], v[0:1], v[0:1]
	v_pk_mov_b32 v[38:39], v[0:1], v[0:1]
	v_pk_mov_b32 v[44:45], v[0:1], v[0:1]
	v_pk_mov_b32 v[46:47], v[0:1], v[0:1]
	v_pk_mov_b32 v[52:53], v[0:1], v[0:1]
	v_pk_mov_b32 v[54:55], v[0:1], v[0:1]
	v_pk_mov_b32 v[56:57], v[0:1], v[0:1]
	v_pk_mov_b32 v[58:59], v[0:1], v[0:1]
	v_pk_mov_b32 v[60:61], v[0:1], v[0:1]
	v_pk_mov_b32 v[62:63], v[0:1], v[0:1]
	v_pk_mov_b32 v[64:65], v[0:1], v[0:1]
	v_pk_mov_b32 v[66:67], v[0:1], v[0:1]
	v_pk_mov_b32 v[68:69], v[0:1], v[0:1]
	v_pk_mov_b32 v[70:71], v[0:1], v[0:1]
	v_pk_mov_b32 v[72:73], v[0:1], v[0:1]
	v_pk_mov_b32 v[74:75], v[0:1], v[0:1]
	v_pk_mov_b32 v[80:81], v[0:1], v[0:1]
	v_pk_mov_b32 v[82:83], v[0:1], v[0:1]
	v_pk_mov_b32 v[88:89], v[0:1], v[0:1]
	v_pk_mov_b32 v[90:91], v[0:1], v[0:1]
	v_pk_mov_b32 v[96:97], v[0:1], v[0:1]
	v_pk_mov_b32 v[98:99], v[0:1], v[0:1]
	v_pk_mov_b32 v[104:105], v[0:1], v[0:1]
	v_pk_mov_b32 v[106:107], v[0:1], v[0:1]
	v_pk_mov_b32 v[112:113], v[0:1], v[0:1]
	v_pk_mov_b32 v[114:115], v[0:1], v[0:1]
	v_pk_mov_b32 v[76:77], v[0:1], v[0:1]
	v_pk_mov_b32 v[78:79], v[0:1], v[0:1]
	v_pk_mov_b32 v[84:85], v[0:1], v[0:1]
	v_pk_mov_b32 v[86:87], v[0:1], v[0:1]
	v_pk_mov_b32 v[92:93], v[0:1], v[0:1]
	v_pk_mov_b32 v[94:95], v[0:1], v[0:1]
	v_pk_mov_b32 v[100:101], v[0:1], v[0:1]
	v_pk_mov_b32 v[102:103], v[0:1], v[0:1]
	v_pk_mov_b32 v[108:109], v[0:1], v[0:1]
	v_pk_mov_b32 v[110:111], v[0:1], v[0:1]
	v_pk_mov_b32 v[116:117], v[0:1], v[0:1]
	v_pk_mov_b32 v[118:119], v[0:1], v[0:1]
	v_pk_mov_b32 v[120:121], v[0:1], v[0:1]
	v_pk_mov_b32 v[122:123], v[0:1], v[0:1]
	v_pk_mov_b32 v[124:125], v[0:1], v[0:1]
	v_pk_mov_b32 v[126:127], v[0:1], v[0:1]

; template <class Epi, class Sched, bool ALIGN_EPI = false, bool SP2 = false>
; __device__ __forceinline__ void gemm_phase(PG8_LAS unsigned char* lds, const Gemm g, const Sched& S, const Epi& E, const int wave0) {
;     ...
;         for (int t = 0; t < nt; t += 2) {
;             const bool last = (t == nt - 2);
;             const char* a1 = cA + (size_t)(t + 1) * kstep;
;             const char* a2 = last ? nA : cA + (size_t)(t + 2) * kstep; const char* b2 = last ? nB : cB + (size_t)(t + 2) * kstep;
;             const char* a3 = a2 + kstep; const char* b3 = b2 + kstep;
;     ...
; #pragma unroll
;         for (int a = 0; a < 2; ++a)
; #pragma unroll
;             for (int b = 0; b < 2; ++b)
; #pragma unroll
;                 for (int m = 0; m < 4; ++m)
; #pragma unroll
;                     for (int n = 0; n < 2; ++n) acc[a][b][m][n] = (f32x4){0.f, 0.f, 0.f, 0.f};
.LBB0_865:
	s_add_u32 s45, s50, 0x100
	s_addc_u32 s76, s51, 0
	s_add_u32 s77, s48, 0x100
	s_addc_u32 s6, s49, 0
	s_add_u32 s48, s50, 0x80080
	v_mov_b32_e32 v0, 0
	s_addc_u32 s49, s51, 0
	s_mov_b32 s7, -2
	v_mov_b32_e32 v1, v0
	v_pk_mov_b32 v[2:3], v[0:1], v[0:1]
	v_pk_mov_b32 v[4:5], v[0:1], v[0:1]
	v_pk_mov_b32 v[6:7], v[0:1], v[0:1]
	v_pk_mov_b32 v[8:9], v[0:1], v[0:1]
	v_pk_mov_b32 v[10:11], v[0:1], v[0:1]
	v_pk_mov_b32 v[16:17], v[0:1], v[0:1]
	v_pk_mov_b32 v[18:19], v[0:1], v[0:1]
	v_pk_mov_b32 v[24:25], v[0:1], v[0:1]
	v_pk_mov_b32 v[26:27], v[0:1], v[0:1]
	v_pk_mov_b32 v[32:33], v[0:1], v[0:1]
	v_pk_mov_b32 v[34:35], v[0:1], v[0:1]
	v_pk_mov_b32 v[40:41], v[0:1], v[0:1]
	v_pk_mov_b32 v[42:43], v[0:1], v[0:1]
	v_pk_mov_b32 v[48:49], v[0:1], v[0:1]
	v_pk_mov_b32 v[50:51], v[0:1], v[0:1]
	v_pk_mov_b32 v[12:13], v[0:1], v[0:1]
	v_pk_mov_b32 v[14:15], v[0:1], v[0:1]
	v_pk_mov_b32 v[20:21], v[0:1], v[0:1]
	v_pk_mov_b32 v[22:23], v[0:1], v[0:1]
	v_pk_mov_b32 v[28:29], v[0:1], v[0:1]
	v_pk_mov_b32 v[30:31], v[0:1], v[0:1]
	v_pk_mov_b32 v[36:37], v[0:1], v[0:1]
	v_pk_mov_b32 v[38:39], v[0:1], v[0:1]
	v_pk_mov_b32 v[44:45], v[0:1], v[0:1]
	v_pk_mov_b32 v[46:47], v[0:1], v[0:1]
	v_pk_mov_b32 v[52:53], v[0:1], v[0:1]
	v_pk_mov_b32 v[54:55], v[0:1], v[0:1]
	v_pk_mov_b32 v[56:57], v[0:1], v[0:1]
	v_pk_mov_b32 v[58:59], v[0:1], v[0:1]
	v_pk_mov_b32 v[60:61], v[0:1], v[0:1]
	v_pk_mov_b32 v[62:63], v[0:1], v[0:1]
	v_pk_mov_b32 v[64:65], v[0:1], v[0:1]
	v_pk_mov_b32 v[66:67], v[0:1], v[0:1]
	v_pk_mov_b32 v[68:69], v[0:1], v[0:1]
	v_pk_mov_b32 v[70:71], v[0:1], v[0:1]
	v_pk_mov_b32 v[72:73], v[0:1], v[0:1]
	v_pk_mov_b32 v[74:75], v[0:1], v[0:1]
	v_pk_mov_b32 v[80:81], v[0:1], v[0:1]
	v_pk_mov_b32 v[82:83], v[0:1], v[0:1]
	v_pk_mov_b32 v[88:89], v[0:1], v[0:1]
	v_pk_mov_b32 v[90:91], v[0:1], v[0:1]
	v_pk_mov_b32 v[96:97], v[0:1], v[0:1]
	v_pk_mov_b32 v[98:99], v[0:1], v[0:1]
	v_pk_mov_b32 v[104:105], v[0:1], v[0:1]
	v_pk_mov_b32 v[106:107], v[0:1], v[0:1]
	v_pk_mov_b32 v[112:113], v[0:1], v[0:1]
	v_pk_mov_b32 v[114:115], v[0:1], v[0:1]
	v_pk_mov_b32 v[76:77], v[0:1], v[0:1]
	v_pk_mov_b32 v[78:79], v[0:1], v[0:1]
	v_pk_mov_b32 v[84:85], v[0:1], v[0:1]
	v_pk_mov_b32 v[86:87], v[0:1], v[0:1]
	v_pk_mov_b32 v[92:93], v[0:1], v[0:1]
	v_pk_mov_b32 v[94:95], v[0:1], v[0:1]
	v_pk_mov_b32 v[100:101], v[0:1], v[0:1]
	v_pk_mov_b32 v[102:103], v[0:1], v[0:1]
	v_pk_mov_b32 v[108:109], v[0:1], v[0:1]
	v_pk_mov_b32 v[110:111], v[0:1], v[0:1]
	v_pk_mov_b32 v[116:117], v[0:1], v[0:1]
	v_pk_mov_b32 v[118:119], v[0:1], v[0:1]
	v_pk_mov_b32 v[120:121], v[0:1], v[0:1]
	v_pk_mov_b32 v[122:123], v[0:1], v[0:1]
	v_pk_mov_b32 v[124:125], v[0:1], v[0:1]
	v_pk_mov_b32 v[126:127], v[0:1], v[0:1]

; template <class Epi, class Sched, bool ALIGN_EPI = false, bool SP2 = false>
; __device__ __forceinline__ void gemm_phase(PG8_LAS unsigned char* lds, const Gemm g, const Sched& S, const Epi& E, const int wave0) {
;     ...
;         for (int t = 0; t < nt; t += 2) {
;             const bool last = (t == nt - 2);
;             const char* a1 = cA + (size_t)(t + 1) * kstep;
;             const char* a2 = last ? nA : cA + (size_t)(t + 2) * kstep; const char* b2 = last ? nB : cB + (size_t)(t + 2) * kstep;
;             const char* a3 = a2 + kstep; const char* b3 = b2 + kstep;
;     ...
; #pragma unroll
;         for (int a = 0; a < 2; ++a)
; #pragma unroll
;             for (int b = 0; b < 2; ++b)
; #pragma unroll
;                 for (int m = 0; m < 4; ++m)
; #pragma unroll
;                     for (int n = 0; n < 2; ++n) acc[a][b][m][n] = (f32x4){0.f, 0.f, 0.f, 0.f};
.LBB0_890:
	s_add_u32 s21, s52, 0x100
	s_addc_u32 s76, s53, 0
	s_add_u32 s77, s50, 0x100
	s_addc_u32 s6, s51, 0
	s_add_u32 s50, s52, 0x80080
	v_mov_b32_e32 v0, 0
	s_addc_u32 s51, s53, 0
	s_mov_b32 s7, -2
	v_mov_b32_e32 v1, v0
	v_pk_mov_b32 v[2:3], v[0:1], v[0:1]
	v_pk_mov_b32 v[4:5], v[0:1], v[0:1]
	v_pk_mov_b32 v[6:7], v[0:1], v[0:1]
	v_pk_mov_b32 v[8:9], v[0:1], v[0:1]
	v_pk_mov_b32 v[10:11], v[0:1], v[0:1]
	v_pk_mov_b32 v[12:13], v[0:1], v[0:1]
	v_pk_mov_b32 v[14:15], v[0:1], v[0:1]
	v_pk_mov_b32 v[24:25], v[0:1], v[0:1]
	v_pk_mov_b32 v[26:27], v[0:1], v[0:1]
	v_pk_mov_b32 v[28:29], v[0:1], v[0:1]
	v_pk_mov_b32 v[30:31], v[0:1], v[0:1]
	v_pk_mov_b32 v[40:41], v[0:1], v[0:1]
	v_pk_mov_b32 v[42:43], v[0:1], v[0:1]
	v_pk_mov_b32 v[44:45], v[0:1], v[0:1]
	v_pk_mov_b32 v[46:47], v[0:1], v[0:1]
	v_pk_mov_b32 v[16:17], v[0:1], v[0:1]
	v_pk_mov_b32 v[18:19], v[0:1], v[0:1]
	v_pk_mov_b32 v[20:21], v[0:1], v[0:1]
	v_pk_mov_b32 v[22:23], v[0:1], v[0:1]
	v_pk_mov_b32 v[32:33], v[0:1], v[0:1]
	v_pk_mov_b32 v[34:35], v[0:1], v[0:1]
	v_pk_mov_b32 v[36:37], v[0:1], v[0:1]
	v_pk_mov_b32 v[38:39], v[0:1], v[0:1]
	v_pk_mov_b32 v[48:49], v[0:1], v[0:1]
	v_pk_mov_b32 v[50:51], v[0:1], v[0:1]
	v_pk_mov_b32 v[52:53], v[0:1], v[0:1]
	v_pk_mov_b32 v[54:55], v[0:1], v[0:1]
	v_pk_mov_b32 v[56:57], v[0:1], v[0:1]
	v_pk_mov_b32 v[58:59], v[0:1], v[0:1]
	v_pk_mov_b32 v[60:61], v[0:1], v[0:1]
	v_pk_mov_b32 v[62:63], v[0:1], v[0:1]
	v_pk_mov_b32 v[64:65], v[0:1], v[0:1]
	v_pk_mov_b32 v[66:67], v[0:1], v[0:1]
	v_pk_mov_b32 v[68:69], v[0:1], v[0:1]
	v_pk_mov_b32 v[70:71], v[0:1], v[0:1]
	v_pk_mov_b32 v[72:73], v[0:1], v[0:1]
	v_pk_mov_b32 v[74:75], v[0:1], v[0:1]
	v_pk_mov_b32 v[76:77], v[0:1], v[0:1]
	v_pk_mov_b32 v[78:79], v[0:1], v[0:1]
	v_pk_mov_b32 v[84:85], v[0:1], v[0:1]
	v_pk_mov_b32 v[86:87], v[0:1], v[0:1]
	v_pk_mov_b32 v[92:93], v[0:1], v[0:1]
	v_pk_mov_b32 v[94:95], v[0:1], v[0:1]
	v_pk_mov_b32 v[100:101], v[0:1], v[0:1]
	v_pk_mov_b32 v[102:103], v[0:1], v[0:1]
	v_pk_mov_b32 v[108:109], v[0:1], v[0:1]
	v_pk_mov_b32 v[110:111], v[0:1], v[0:1]
	v_pk_mov_b32 v[80:81], v[0:1], v[0:1]
	v_pk_mov_b32 v[82:83], v[0:1], v[0:1]
	v_pk_mov_b32 v[88:89], v[0:1], v[0:1]
	v_pk_mov_b32 v[90:91], v[0:1], v[0:1]
	v_pk_mov_b32 v[96:97], v[0:1], v[0:1]
	v_pk_mov_b32 v[98:99], v[0:1], v[0:1]
	v_pk_mov_b32 v[104:105], v[0:1], v[0:1]
	v_pk_mov_b32 v[106:107], v[0:1], v[0:1]
	v_pk_mov_b32 v[112:113], v[0:1], v[0:1]
	v_pk_mov_b32 v[114:115], v[0:1], v[0:1]
	v_pk_mov_b32 v[116:117], v[0:1], v[0:1]
	v_pk_mov_b32 v[118:119], v[0:1], v[0:1]
	v_pk_mov_b32 v[120:121], v[0:1], v[0:1]
	v_pk_mov_b32 v[122:123], v[0:1], v[0:1]
	v_pk_mov_b32 v[124:125], v[0:1], v[0:1]
	v_pk_mov_b32 v[126:127], v[0:1], v[0:1]

; template <class Epi, class Sched, bool ALIGN_EPI = false, bool SP2 = false>
; __device__ __forceinline__ void gemm_phase(PG8_LAS unsigned char* lds, const Gemm g, const Sched& S, const Epi& E, const int wave0) {
;     ...
;         for (int t = 0; t < nt; t += 2) {
;             const bool last = (t == nt - 2);
;             const char* a1 = cA + (size_t)(t + 1) * kstep;
;             const char* a2 = last ? nA : cA + (size_t)(t + 2) * kstep; const char* b2 = last ? nB : cB + (size_t)(t + 2) * kstep;
;             const char* a3 = a2 + kstep; const char* b3 = b2 + kstep;
;     ...
; #pragma unroll
;         for (int a = 0; a < 2; ++a)
; #pragma unroll
;             for (int b = 0; b < 2; ++b)
; #pragma unroll
;                 for (int m = 0; m < 4; ++m)
; #pragma unroll
;                     for (int n = 0; n < 2; ++n) acc[a][b][m][n] = (f32x4){0.f, 0.f, 0.f, 0.f};
.LBB0_1035:
	s_add_u32 s5, s60, 0x100
	s_addc_u32 s53, s61, 0
	s_add_u32 s57, s58, 0x100
	s_addc_u32 s6, s59, 0
	s_add_u32 s58, s60, 0x80080
	v_mov_b32_e32 v0, 0
	s_addc_u32 s59, s61, 0
	s_mov_b32 s7, -2
	v_mov_b32_e32 v1, v0
	v_pk_mov_b32 v[2:3], v[0:1], v[0:1]
	v_pk_mov_b32 v[8:9], v[0:1], v[0:1]
	v_pk_mov_b32 v[10:11], v[0:1], v[0:1]
	v_pk_mov_b32 v[16:17], v[0:1], v[0:1]
	v_pk_mov_b32 v[18:19], v[0:1], v[0:1]
	v_pk_mov_b32 v[24:25], v[0:1], v[0:1]
	v_pk_mov_b32 v[26:27], v[0:1], v[0:1]
	v_pk_mov_b32 v[32:33], v[0:1], v[0:1]
	v_pk_mov_b32 v[34:35], v[0:1], v[0:1]
	v_pk_mov_b32 v[40:41], v[0:1], v[0:1]
	v_pk_mov_b32 v[42:43], v[0:1], v[0:1]
	v_pk_mov_b32 v[48:49], v[0:1], v[0:1]
	v_pk_mov_b32 v[50:51], v[0:1], v[0:1]
	v_pk_mov_b32 v[56:57], v[0:1], v[0:1]
	v_pk_mov_b32 v[58:59], v[0:1], v[0:1]
	v_pk_mov_b32 v[4:5], v[0:1], v[0:1]
	v_pk_mov_b32 v[6:7], v[0:1], v[0:1]
	v_pk_mov_b32 v[12:13], v[0:1], v[0:1]
	v_pk_mov_b32 v[14:15], v[0:1], v[0:1]
	v_pk_mov_b32 v[20:21], v[0:1], v[0:1]
	v_pk_mov_b32 v[22:23], v[0:1], v[0:1]
	v_pk_mov_b32 v[28:29], v[0:1], v[0:1]
	v_pk_mov_b32 v[30:31], v[0:1], v[0:1]
	v_pk_mov_b32 v[36:37], v[0:1], v[0:1]
	v_pk_mov_b32 v[38:39], v[0:1], v[0:1]
	v_pk_mov_b32 v[44:45], v[0:1], v[0:1]
	v_pk_mov_b32 v[46:47], v[0:1], v[0:1]
	v_pk_mov_b32 v[52:53], v[0:1], v[0:1]
	v_pk_mov_b32 v[54:55], v[0:1], v[0:1]
	v_pk_mov_b32 v[60:61], v[0:1], v[0:1]
	v_pk_mov_b32 v[62:63], v[0:1], v[0:1]
	v_pk_mov_b32 v[64:65], v[0:1], v[0:1]
	v_pk_mov_b32 v[66:67], v[0:1], v[0:1]
	v_pk_mov_b32 v[72:73], v[0:1], v[0:1]
	v_pk_mov_b32 v[74:75], v[0:1], v[0:1]
	v_pk_mov_b32 v[80:81], v[0:1], v[0:1]
	v_pk_mov_b32 v[82:83], v[0:1], v[0:1]
	v_pk_mov_b32 v[88:89], v[0:1], v[0:1]
	v_pk_mov_b32 v[90:91], v[0:1], v[0:1]
	v_pk_mov_b32 v[96:97], v[0:1], v[0:1]
	v_pk_mov_b32 v[98:99], v[0:1], v[0:1]
	v_pk_mov_b32 v[104:105], v[0:1], v[0:1]
	v_pk_mov_b32 v[106:107], v[0:1], v[0:1]
	v_pk_mov_b32 v[112:113], v[0:1], v[0:1]
	v_pk_mov_b32 v[114:115], v[0:1], v[0:1]
	v_pk_mov_b32 v[120:121], v[0:1], v[0:1]
	v_pk_mov_b32 v[122:123], v[0:1], v[0:1]
	v_pk_mov_b32 v[68:69], v[0:1], v[0:1]
	v_pk_mov_b32 v[70:71], v[0:1], v[0:1]
	v_pk_mov_b32 v[76:77], v[0:1], v[0:1]
	v_pk_mov_b32 v[78:79], v[0:1], v[0:1]
	v_pk_mov_b32 v[84:85], v[0:1], v[0:1]
	v_pk_mov_b32 v[86:87], v[0:1], v[0:1]
	v_pk_mov_b32 v[92:93], v[0:1], v[0:1]
	v_pk_mov_b32 v[94:95], v[0:1], v[0:1]
	v_pk_mov_b32 v[100:101], v[0:1], v[0:1]
	v_pk_mov_b32 v[102:103], v[0:1], v[0:1]
	v_pk_mov_b32 v[108:109], v[0:1], v[0:1]
	v_pk_mov_b32 v[110:111], v[0:1], v[0:1]
	v_pk_mov_b32 v[116:117], v[0:1], v[0:1]
	v_pk_mov_b32 v[118:119], v[0:1], v[0:1]
	v_pk_mov_b32 v[124:125], v[0:1], v[0:1]
	v_pk_mov_b32 v[126:127], v[0:1], v[0:1]

; template <class Epi, class Sched, bool ALIGN_EPI = false, bool SP2 = false>
; __device__ __forceinline__ void gemm_phase(PG8_LAS unsigned char* lds, const Gemm g, const Sched& S, const Epi& E, const int wave0) {
;     ...
;         for (int t = 0; t < nt; t += 2) {
;             const bool last = (t == nt - 2);
;             const char* a1 = cA + (size_t)(t + 1) * kstep;
;             const char* a2 = last ? nA : cA + (size_t)(t + 2) * kstep; const char* b2 = last ? nB : cB + (size_t)(t + 2) * kstep;
;             const char* a3 = a2 + kstep; const char* b3 = b2 + kstep;
;     ...
; #pragma unroll
;         for (int a = 0; a < 2; ++a)
; #pragma unroll
;             for (int b = 0; b < 2; ++b)
; #pragma unroll
;                 for (int m = 0; m < 4; ++m)
; #pragma unroll
;                     for (int n = 0; n < 2; ++n) acc[a][b][m][n] = (f32x4){0.f, 0.f, 0.f, 0.f};
.LBB0_1111:
	s_add_u32 s76, s54, 0x100
	s_addc_u32 s77, s55, 0
	s_add_u32 s88, s52, 0x100
	s_addc_u32 s6, s53, 0
	s_add_u32 s52, s54, 0x160080
	v_mov_b32_e32 v0, 0
	s_addc_u32 s53, s55, 0
	s_mov_b32 s7, -2
	v_mov_b32_e32 v1, v0
	v_pk_mov_b32 v[2:3], v[0:1], v[0:1]
	v_pk_mov_b32 v[4:5], v[0:1], v[0:1]
	v_pk_mov_b32 v[6:7], v[0:1], v[0:1]
	v_pk_mov_b32 v[8:9], v[0:1], v[0:1]
	v_pk_mov_b32 v[10:11], v[0:1], v[0:1]
	v_pk_mov_b32 v[16:17], v[0:1], v[0:1]
	v_pk_mov_b32 v[18:19], v[0:1], v[0:1]
	v_pk_mov_b32 v[24:25], v[0:1], v[0:1]
	v_pk_mov_b32 v[26:27], v[0:1], v[0:1]
	v_pk_mov_b32 v[32:33], v[0:1], v[0:1]
	v_pk_mov_b32 v[34:35], v[0:1], v[0:1]
	v_pk_mov_b32 v[40:41], v[0:1], v[0:1]
	v_pk_mov_b32 v[42:43], v[0:1], v[0:1]
	v_pk_mov_b32 v[48:49], v[0:1], v[0:1]
	v_pk_mov_b32 v[50:51], v[0:1], v[0:1]
	v_pk_mov_b32 v[12:13], v[0:1], v[0:1]
	v_pk_mov_b32 v[14:15], v[0:1], v[0:1]
	v_pk_mov_b32 v[20:21], v[0:1], v[0:1]
	v_pk_mov_b32 v[22:23], v[0:1], v[0:1]
	v_pk_mov_b32 v[28:29], v[0:1], v[0:1]
	v_pk_mov_b32 v[30:31], v[0:1], v[0:1]
	v_pk_mov_b32 v[36:37], v[0:1], v[0:1]
	v_pk_mov_b32 v[38:39], v[0:1], v[0:1]
	v_pk_mov_b32 v[44:45], v[0:1], v[0:1]
	v_pk_mov_b32 v[46:47], v[0:1], v[0:1]
	v_pk_mov_b32 v[52:53], v[0:1], v[0:1]
	v_pk_mov_b32 v[54:55], v[0:1], v[0:1]
	v_pk_mov_b32 v[56:57], v[0:1], v[0:1]
	v_pk_mov_b32 v[58:59], v[0:1], v[0:1]
	v_pk_mov_b32 v[60:61], v[0:1], v[0:1]
	v_pk_mov_b32 v[62:63], v[0:1], v[0:1]
	v_pk_mov_b32 v[64:65], v[0:1], v[0:1]
	v_pk_mov_b32 v[66:67], v[0:1], v[0:1]
	v_pk_mov_b32 v[68:69], v[0:1], v[0:1]
	v_pk_mov_b32 v[70:71], v[0:1], v[0:1]
	v_pk_mov_b32 v[72:73], v[0:1], v[0:1]
	v_pk_mov_b32 v[74:75], v[0:1], v[0:1]
	v_pk_mov_b32 v[80:81], v[0:1], v[0:1]
	v_pk_mov_b32 v[82:83], v[0:1], v[0:1]
	v_pk_mov_b32 v[88:89], v[0:1], v[0:1]
	v_pk_mov_b32 v[90:91], v[0:1], v[0:1]
	v_pk_mov_b32 v[96:97], v[0:1], v[0:1]
	v_pk_mov_b32 v[98:99], v[0:1], v[0:1]
	v_pk_mov_b32 v[104:105], v[0:1], v[0:1]
	v_pk_mov_b32 v[106:107], v[0:1], v[0:1]
	v_pk_mov_b32 v[112:113], v[0:1], v[0:1]
	v_pk_mov_b32 v[114:115], v[0:1], v[0:1]
	v_pk_mov_b32 v[76:77], v[0:1], v[0:1]
	v_pk_mov_b32 v[78:79], v[0:1], v[0:1]
	v_pk_mov_b32 v[84:85], v[0:1], v[0:1]
	v_pk_mov_b32 v[86:87], v[0:1], v[0:1]
	v_pk_mov_b32 v[92:93], v[0:1], v[0:1]
	v_pk_mov_b32 v[94:95], v[0:1], v[0:1]
	v_pk_mov_b32 v[100:101], v[0:1], v[0:1]
	v_pk_mov_b32 v[102:103], v[0:1], v[0:1]
	v_pk_mov_b32 v[108:109], v[0:1], v[0:1]
	v_pk_mov_b32 v[110:111], v[0:1], v[0:1]
	v_pk_mov_b32 v[116:117], v[0:1], v[0:1]
	v_pk_mov_b32 v[118:119], v[0:1], v[0:1]
	v_pk_mov_b32 v[120:121], v[0:1], v[0:1]
	v_pk_mov_b32 v[122:123], v[0:1], v[0:1]
	v_pk_mov_b32 v[124:125], v[0:1], v[0:1]
	v_pk_mov_b32 v[126:127], v[0:1], v[0:1]

; template <class Epi, class Sched, bool ALIGN_EPI = false, bool SP2 = false>
; __device__ __forceinline__ void gemm_phase(PG8_LAS unsigned char* lds, const Gemm g, const Sched& S, const Epi& E, const int wave0) {
;     ...
;         for (int t = 0; t < nt; t += 2) {
;             const bool last = (t == nt - 2);
;             const char* a1 = cA + (size_t)(t + 1) * kstep;
;             const char* a2 = last ? nA : cA + (size_t)(t + 2) * kstep; const char* b2 = last ? nB : cB + (size_t)(t + 2) * kstep;
;             const char* a3 = a2 + kstep; const char* b3 = b2 + kstep;
;     ...
; #pragma unroll
;         for (int a = 0; a < 2; ++a)
; #pragma unroll
;             for (int b = 0; b < 2; ++b)
; #pragma unroll
;                 for (int m = 0; m < 4; ++m)
; #pragma unroll
;                     for (int n = 0; n < 2; ++n) acc[a][b][m][n] = (f32x4){0.f, 0.f, 0.f, 0.f};
.LBB0_1136:
	s_add_u32 s76, s46, 0x100
	s_addc_u32 s77, s47, 0
	s_add_u32 s88, s44, 0x100
	s_addc_u32 s6, s45, 0
	s_add_u32 s44, s46, 0x160080
	v_mov_b32_e32 v0, 0
	s_addc_u32 s45, s47, 0
	s_mov_b32 s7, -2
	v_mov_b32_e32 v1, v0
	v_pk_mov_b32 v[2:3], v[0:1], v[0:1]
	v_pk_mov_b32 v[4:5], v[0:1], v[0:1]
	v_pk_mov_b32 v[6:7], v[0:1], v[0:1]
	v_pk_mov_b32 v[8:9], v[0:1], v[0:1]
	v_pk_mov_b32 v[10:11], v[0:1], v[0:1]
	v_pk_mov_b32 v[12:13], v[0:1], v[0:1]
	v_pk_mov_b32 v[14:15], v[0:1], v[0:1]
	v_pk_mov_b32 v[24:25], v[0:1], v[0:1]
	v_pk_mov_b32 v[26:27], v[0:1], v[0:1]
	v_pk_mov_b32 v[28:29], v[0:1], v[0:1]
	v_pk_mov_b32 v[30:31], v[0:1], v[0:1]
	v_pk_mov_b32 v[40:41], v[0:1], v[0:1]
	v_pk_mov_b32 v[42:43], v[0:1], v[0:1]
	v_pk_mov_b32 v[44:45], v[0:1], v[0:1]
	v_pk_mov_b32 v[46:47], v[0:1], v[0:1]
	v_pk_mov_b32 v[16:17], v[0:1], v[0:1]
	v_pk_mov_b32 v[18:19], v[0:1], v[0:1]
	v_pk_mov_b32 v[20:21], v[0:1], v[0:1]
	v_pk_mov_b32 v[22:23], v[0:1], v[0:1]
	v_pk_mov_b32 v[32:33], v[0:1], v[0:1]
	v_pk_mov_b32 v[34:35], v[0:1], v[0:1]
	v_pk_mov_b32 v[36:37], v[0:1], v[0:1]
	v_pk_mov_b32 v[38:39], v[0:1], v[0:1]
	v_pk_mov_b32 v[48:49], v[0:1], v[0:1]
	v_pk_mov_b32 v[50:51], v[0:1], v[0:1]
	v_pk_mov_b32 v[52:53], v[0:1], v[0:1]
	v_pk_mov_b32 v[54:55], v[0:1], v[0:1]
	v_pk_mov_b32 v[56:57], v[0:1], v[0:1]
	v_pk_mov_b32 v[58:59], v[0:1], v[0:1]
	v_pk_mov_b32 v[60:61], v[0:1], v[0:1]
	v_pk_mov_b32 v[62:63], v[0:1], v[0:1]
	v_pk_mov_b32 v[64:65], v[0:1], v[0:1]
	v_pk_mov_b32 v[66:67], v[0:1], v[0:1]
	v_pk_mov_b32 v[68:69], v[0:1], v[0:1]
	v_pk_mov_b32 v[70:71], v[0:1], v[0:1]
	v_pk_mov_b32 v[72:73], v[0:1], v[0:1]
	v_pk_mov_b32 v[74:75], v[0:1], v[0:1]
	v_pk_mov_b32 v[76:77], v[0:1], v[0:1]
	v_pk_mov_b32 v[78:79], v[0:1], v[0:1]
	v_pk_mov_b32 v[84:85], v[0:1], v[0:1]
	v_pk_mov_b32 v[86:87], v[0:1], v[0:1]
	v_pk_mov_b32 v[92:93], v[0:1], v[0:1]
	v_pk_mov_b32 v[94:95], v[0:1], v[0:1]
	v_pk_mov_b32 v[100:101], v[0:1], v[0:1]
	v_pk_mov_b32 v[102:103], v[0:1], v[0:1]
	v_pk_mov_b32 v[108:109], v[0:1], v[0:1]
	v_pk_mov_b32 v[110:111], v[0:1], v[0:1]
	v_pk_mov_b32 v[80:81], v[0:1], v[0:1]
	v_pk_mov_b32 v[82:83], v[0:1], v[0:1]
	v_pk_mov_b32 v[88:89], v[0:1], v[0:1]
	v_pk_mov_b32 v[90:91], v[0:1], v[0:1]
	v_pk_mov_b32 v[96:97], v[0:1], v[0:1]
	v_pk_mov_b32 v[98:99], v[0:1], v[0:1]
	v_pk_mov_b32 v[104:105], v[0:1], v[0:1]
	v_pk_mov_b32 v[106:107], v[0:1], v[0:1]
	v_pk_mov_b32 v[112:113], v[0:1], v[0:1]
	v_pk_mov_b32 v[114:115], v[0:1], v[0:1]
	v_pk_mov_b32 v[116:117], v[0:1], v[0:1]
	v_pk_mov_b32 v[118:119], v[0:1], v[0:1]
	v_pk_mov_b32 v[120:121], v[0:1], v[0:1]
	v_pk_mov_b32 v[122:123], v[0:1], v[0:1]
	v_pk_mov_b32 v[124:125], v[0:1], v[0:1]
	v_pk_mov_b32 v[126:127], v[0:1], v[0:1]
